# x16 + fused epilogues (GOUT, F2): the 8 serial sc1 slot loads (load, wait, add x8) replaced by two dwordx4 sc1 loads, same add order
# baseline (speedup 1.0000x reference)
;     __device__ __forceinline__ void fused(f32x4 (&acc)[2][2][4][2], const Unit& u, int wr, int wc, int fr, int fq, PG8_LAS unsigned char* lds, int wid, int lane) const {
;     ...
;         if (wid < 4) {
;             const unsigned* sp = (const unsigned*)slots + (size_t)(u.pm * BM + prow) * 8; float t = 0.f;
; #pragma unroll
;             for (int k = 0; k < 8; ++k) t += __uint_as_float(__hip_atomic_load(sp + k, __ATOMIC_RELAXED, __HIP_MEMORY_SCOPE_AGENT));
;             St[prow] = rsqrtf(t * (1.0f / DM) + EPS);
;         }
.LBB0_1117:
	s_waitcnt vmcnt(0) lgkmcnt(0)
	s_barrier
	s_andn2_b64 vcc, exec, s[46:47]
	s_cbranch_vccnz .LBB0_1119
	v_lshlrev_b64 v[162:163], 5, v[162:163]
	v_lshl_add_u64 v[162:163], s[38:39], 0, v[162:163]
	global_load_dwordx4 v[168:171], v[162:163], off sc1
	global_load_dwordx4 v[172:175], v[162:163], off offset:16 sc1
	s_waitcnt vmcnt(1)
	v_add_f32_e32 v96, 0, v168
	v_add_f32_e32 v96, v96, v169
	v_add_f32_e32 v96, v96, v170
	v_add_f32_e32 v96, v96, v171
	s_waitcnt vmcnt(0)
	v_add_f32_e32 v96, v96, v172
	v_add_f32_e32 v96, v96, v173
	v_add_f32_e32 v96, v96, v174
	v_add_f32_e32 v96, v96, v175
	v_fmamk_f32 v96, v96, 0x3a000000, v198
	v_cmp_gt_f32_e32 vcc, s33, v96
	v_mul_f32_e32 v162, 0x4b800000, v96
	s_nop 0
	v_cndmask_b32_e32 v96, v96, v162, vcc
	v_rsq_f32_e32 v96, v96
	s_nop 0
	v_mul_f32_e32 v162, 0x45800000, v96
	v_cndmask_b32_e32 v96, v96, v162, vcc
	v_lshl_add_u32 v162, v164, 2, 0
	ds_write_b32 v162, v96 offset:8192

;     __device__ __forceinline__ void fused(f32x4 (&acc)[2][2][4][2], const Unit& u, int wr, int wc, int fr, int fq, PG8_LAS unsigned char* lds, int wid, int lane) const {
;     ...
;         if (wid < 4) {
;             const unsigned* sp = (const unsigned*)slots + (size_t)(u.pm * BM + prow) * 8; float t = 0.f;
; #pragma unroll
;             for (int k = 0; k < 8; ++k) t += __uint_as_float(__hip_atomic_load(sp + k, __ATOMIC_RELAXED, __HIP_MEMORY_SCOPE_AGENT));
;             St[prow] = rsqrtf(t * (1.0f / DM) + EPS);
;         }
.LBB0_1563:
	s_waitcnt vmcnt(0) lgkmcnt(0)
	s_barrier
	s_andn2_b64 vcc, exec, s[56:57]
	s_cbranch_vccnz .LBB0_1565
	v_lshlrev_b64 v[162:163], 5, v[162:163]
	v_lshl_add_u64 v[162:163], s[50:51], 0, v[162:163]
	global_load_dwordx4 v[168:171], v[162:163], off sc1
	global_load_dwordx4 v[172:175], v[162:163], off offset:16 sc1
	s_waitcnt vmcnt(1)
	v_add_f32_e32 v96, 0, v168
	v_add_f32_e32 v96, v96, v169
	v_add_f32_e32 v96, v96, v170
	v_add_f32_e32 v96, v96, v171
	s_waitcnt vmcnt(0)
	v_add_f32_e32 v96, v96, v172
	v_add_f32_e32 v96, v96, v173
	v_add_f32_e32 v96, v96, v174
	v_add_f32_e32 v96, v96, v175
	v_fmamk_f32 v96, v96, 0x3a000000, v198
	v_cmp_gt_f32_e32 vcc, s33, v96
	v_mul_f32_e32 v162, 0x4b800000, v96
	s_nop 0
	v_cndmask_b32_e32 v96, v96, v162, vcc
	v_rsq_f32_e32 v96, v96
	s_nop 0
	v_mul_f32_e32 v162, 0x45800000, v96
	v_cndmask_b32_e32 v96, v96, v162, vcc
	v_lshl_add_u32 v162, v164, 2, 0
	ds_write_b32 v162, v96 offset:8192
